# attention fast path: first exp group and V-fragment reads moved under the second half of the row-block-1 QK MFMAs (staging placement as in v71)
# speedup vs baseline: 1.0035x; 1.0035x over previous
; #define LAS __attribute__((address_space(3)))
; __device__ __forceinline__ void unit(unsigned char* ws, LAS unsigned char* lds, int b, int h, int mp, int qb, const int tid_in) {
;     ...
;         for (int jt = 0; jt < 4; ++jt) { const bf16x8 kf0 = *(const LAS bf16x8*)(KS + (16 * jt + fr) * KP + 8 * fq), kf1 = *(const LAS bf16x8*)(KS + (16 * jt + fr) * KP + 32 + 8 * fq);
; #pragma unroll
;             for (int g = 0; g < 2; ++g) { const float nm = -m[g]; s[g][jt] = __builtin_amdgcn_mfma_f32_16x16x32_bf16(kf0, qf[g][0], (f32x4){nm, nm, nm, nm}, 0, 0, 0); s[g][jt] = __builtin_amdgcn_mfma_f32_16x16x32_bf16(kf1, qf[g][1], s[g][jt], 0, 0, 0); } }
;         const bool nearb = (qw0 - (k0 + 63) < 113);
;         bf16x8 pf[2][2];
; #pragma unroll
;         for (int g = 0; g < 2; ++g) {
;             if (nearb) {
;                 const LAS float* tb = TB + (256 + qw0 + 16 * g + fr - (k0 + 4 * fq));
; #pragma unroll
;                 for (int jt = 0; jt < 4; ++jt)
; #pragma unroll
;                     for (int jj = 0; jj < 4; ++jj) { const float bv = tb[-(16 * jt + jj)]; float x = s[g][jt][jj];
;                         asm("v_add_f32_e32 %0, %1, %2" : "=v"(x) : "v"(x), "v"(bv));
;                         s[g][jt][jj] = x; }
;             }
;             float mx = fmaxf(fmaxf(s[g][0][0], s[g][0][1]), fmaxf(s[g][0][2], s[g][0][3]));
; #pragma unroll
;             for (int jt = 1; jt < 4; ++jt) mx = fmaxf(mx, fmaxf(fmaxf(s[g][jt][0], s[g][jt][1]), fmaxf(s[g][jt][2], s[g][jt][3])));
.Lattn_fast:
	s_bitcmp1_b32 s68, 0
	s_cselect_b32 s21, 0, 0x6c00
	v_add_u32_e32 v179, s21, v174
	v_lshl_add_u32 v178, v169, 1, v179
	ds_read_b128 v[222:225], v178
	ds_read_b128 v[226:229], v178 offset:64
	ds_read_b128 v[230:233], v178 offset:2304
	ds_read_b128 v[234:237], v178 offset:2368
	ds_read_b128 v[238:241], v178 offset:4608
	ds_read_b128 v[242:245], v178 offset:4672
	ds_read_b128 v[246:249], v178 offset:6912
	ds_read_b128 v[250:253], v178 offset:6976
	v_xor_b32_e32 v214, 0x80000000, v175
	v_mov_b32_e32 v215, v214
	v_mov_b32_e32 v216, v214
	v_mov_b32_e32 v217, v214
	v_xor_b32_e32 v218, 0x80000000, v177
	v_mov_b32_e32 v219, v218
	v_mov_b32_e32 v220, v218
	v_mov_b32_e32 v221, v218
	s_waitcnt lgkmcnt(7)
	v_mfma_f32_16x16x32_bf16 v[126:129], v[222:225], v[82:85], v[214:217]
	v_lshl_add_u32 v210, v168, 1, v179
	v_lshl_add_u32 v211, v167, 1, v179
	v_lshl_add_u32 v212, v166, 1, v179
	s_waitcnt lgkmcnt(6)
	v_mfma_f32_16x16x32_bf16 v[126:129], v[226:229], v[78:81], v[126:129]
	v_mov_b32_e32 v206, s20
	v_mov_b32_e32 v207, s20
	v_mov_b32_e32 v208, s20
	s_waitcnt lgkmcnt(5)
	v_mfma_f32_16x16x32_bf16 v[130:133], v[230:233], v[82:85], v[214:217]
	v_mov_b32_e32 v209, s20
	s_waitcnt lgkmcnt(4)
	v_mfma_f32_16x16x32_bf16 v[130:133], v[234:237], v[78:81], v[130:133]
	s_waitcnt lgkmcnt(3)
	v_mfma_f32_16x16x32_bf16 v[138:141], v[238:241], v[82:85], v[214:217]
	s_waitcnt lgkmcnt(2)
	v_mfma_f32_16x16x32_bf16 v[138:141], v[242:245], v[78:81], v[138:141]
	s_waitcnt lgkmcnt(1)
	v_mfma_f32_16x16x32_bf16 v[142:145], v[246:249], v[82:85], v[214:217]
	s_waitcnt lgkmcnt(0)
	v_mfma_f32_16x16x32_bf16 v[142:145], v[250:253], v[78:81], v[142:145]
	v_mfma_f32_16x16x32_bf16 v[114:117], v[222:225], v[86:89], v[218:221]
	v_mfma_f32_16x16x32_bf16 v[114:117], v[226:229], v[74:77], v[114:117]
	v_max3_f32 v181, v126, v127, v128
	v_mfma_f32_16x16x32_bf16 v[118:121], v[230:233], v[86:89], v[218:221]
	v_max3_f32 v182, v129, v130, v131
	v_mfma_f32_16x16x32_bf16 v[118:121], v[234:237], v[74:77], v[118:121]
	v_max3_f32 v181, v132, v133, v181
	v_max3_f32 v183, v138, v139, v140
	v_max3_f32 v181, v141, v182, v181
	v_max3_f32 v182, v142, v143, v144
	v_max3_f32 v181, v145, v183, v181
	v_max_f32_e32 v180, v182, v181
	v_cmp_lt_f32_e32 vcc, s94, v180
	s_cbranch_vccnz .Lattn_rare0
